# P6 attention: four-factor segment products with one packed f32 multiply each (reassociated, same f32 roundings count)
# speedup vs baseline: 1.0041x; 1.0008x over previous
; __device__ __forceinline__ void attn_phase(const Ptrs& P, int gw, int NGW, int lane) {
;     ...
;             bf16x8 k3[4], v2[2][2];
;             { const int t3 = kt > 2 ? kt - 3 : 0, t2 = kt > 1 ? kt - 2 : 0;
; #pragma unroll
;               for (int ks = 0; ks < 4; ++ks) k3[ks] = kbase[(size_t)t3 * 256 + ks * 64];
; #pragma unroll
;               for (int dt = 0; dt < 2; ++dt)
; #pragma unroll
;                   for (int s = 0; s < 2; ++s) v2[dt][s] = vbase[(size_t)t2 * 256 + (dt * 2 + s) * 64]; }
;             f32x16 sa;
; #pragma unroll
;             for (int i = 0; i < 16; ++i) sa[i] = 0.f;
; #pragma unroll
;             for (int ks = 0; ks < 4; ++ks) sa = MFMA32(kf[ks], qf[ks], sa);
;             float beta[16], f[16];
;             const bool diag = (kt == qt);
; #pragma unroll
;             for (int i = 0; i < 16; ++i) { float ff = rcpf_(1.0f + ex2(sa[i])), bt = 1.0f - ff;
;                 if (diag) { const bool valid = crow(i, hh) < r; bt = valid ? bt : 0.0f; ff = valid ? ff : 1.0f; }
;                 beta[i] = bt; f[i] = ff; }
;             float gp[4], ot[4], pr[4];
; #pragma unroll
;             for (int g = 0; g < 4; ++g) { gp[g] = (f[4 * g] * f[4 * g + 1]) * (f[4 * g + 2] * f[4 * g + 3]);
;                 const auto rr = __builtin_amdgcn_permlane32_swap(__float_as_uint(gp[g]), __float_as_uint(gp[g]), false, false);
;                 ot[g] = __uint_as_float(rr[1]); pr[g] = __uint_as_float(rr[0]) * __uint_as_float(rr[1]); }
;             float suf = Pc; float att[16];
; #pragma unroll
;             for (int g = 3; g >= 0; --g) { float p = (hh == 0) ? suf * ot[g] : suf;
;                 att[4 * g + 3] = beta[4 * g + 3] * p; p *= f[4 * g + 3];
;                 att[4 * g + 2] = beta[4 * g + 2] * p; p *= f[4 * g + 2];
;                 att[4 * g + 1] = beta[4 * g + 1] * p; p *= f[4 * g + 1];
;                 att[4 * g] = beta[4 * g] * p;
;                 suf *= pr[g]; }
;             Pc = suf;
; #pragma unroll
;             for (int i = 0; i < 16; ++i) asm("" : "+v"(att[i]));
;             bf16x8 pf[2];
; #pragma unroll
;             for (int s = 0; s < 2; ++s) { v4u t; t.x = pk2(att[8 * s], att[8 * s + 1]); t.y = pk2(att[8 * s + 2], att[8 * s + 3]); t.z = pk2(att[8 * s + 4], att[8 * s + 5]); t.w = pk2(att[8 * s + 6], att[8 * s + 7]); pf[s] = __builtin_bit_cast(bf16x8, t); }
; #pragma unroll
.Lp6_unit:
	s_mov_b32 s68, s63
	v_mov_b32_e32 v229, 1.0
	v_mov_b32_e32 v252, 1.0
	v_mov_b32_e32 v253, 1.0
	s_waitcnt vmcnt(20)
	v_mfma_f32_32x32x16_bf16 v[32:47], v[64:67], v[48:51], 0
	v_mfma_f32_32x32x16_bf16 v[32:47], v[68:71], v[52:55], v[32:47]
	v_mfma_f32_32x32x16_bf16 v[32:47], v[72:75], v[56:59], v[32:47]
	v_mfma_f32_32x32x16_bf16 v[32:47], v[76:79], v[60:63], v[32:47]
	s_sub_i32 s80, s68, 3
	s_max_i32 s80, s80, 0
	s_lshl_b32 s80, s80, 12
	s_add_u32 s74, s70, s80
	s_addc_u32 s75, s71, 0
	s_add_u32 s76, s72, s80
	s_addc_u32 s77, s73, 0
	s_nop 4
	v_exp_f32_e32 v32, v32
	v_exp_f32_e32 v33, v33
	v_exp_f32_e32 v34, v34
	v_exp_f32_e32 v35, v35
	v_exp_f32_e32 v36, v36
	v_exp_f32_e32 v37, v37
	v_exp_f32_e32 v38, v38
	v_exp_f32_e32 v39, v39
	v_exp_f32_e32 v40, v40
	v_exp_f32_e32 v41, v41
	v_exp_f32_e32 v42, v42
	v_exp_f32_e32 v43, v43
	v_exp_f32_e32 v44, v44
	v_exp_f32_e32 v45, v45
	v_exp_f32_e32 v46, v46
	v_exp_f32_e32 v47, v47
	v_pk_add_f32 v[32:33], v[32:33], v[252:253] op_sel_hi:[1,0]
	v_pk_add_f32 v[34:35], v[34:35], v[252:253] op_sel_hi:[1,0]
	v_pk_add_f32 v[36:37], v[36:37], v[252:253] op_sel_hi:[1,0]
	v_pk_add_f32 v[38:39], v[38:39], v[252:253] op_sel_hi:[1,0]
	v_pk_add_f32 v[40:41], v[40:41], v[252:253] op_sel_hi:[1,0]
	v_pk_add_f32 v[42:43], v[42:43], v[252:253] op_sel_hi:[1,0]
	v_pk_add_f32 v[44:45], v[44:45], v[252:253] op_sel_hi:[1,0]
	v_pk_add_f32 v[46:47], v[46:47], v[252:253] op_sel_hi:[1,0]
	v_rcp_f32_e32 v32, v32
	v_rcp_f32_e32 v33, v33
	v_rcp_f32_e32 v34, v34
	v_rcp_f32_e32 v35, v35
	v_rcp_f32_e32 v36, v36
	v_rcp_f32_e32 v37, v37
	v_rcp_f32_e32 v38, v38
	v_rcp_f32_e32 v39, v39
	v_rcp_f32_e32 v40, v40
	v_rcp_f32_e32 v41, v41
	v_rcp_f32_e32 v42, v42
	v_rcp_f32_e32 v43, v43
	v_rcp_f32_e32 v44, v44
	v_rcp_f32_e32 v45, v45
	v_rcp_f32_e32 v46, v46
	v_rcp_f32_e32 v47, v47
	v_cndmask_b32_e64 v32, 1.0, v32, s[4:5]
	v_cndmask_b32_e64 v33, 1.0, v33, s[6:7]
	v_cndmask_b32_e64 v34, 1.0, v34, s[8:9]
	v_cndmask_b32_e64 v35, 1.0, v35, s[10:11]
	v_cndmask_b32_e64 v36, 1.0, v36, s[12:13]
	v_cndmask_b32_e64 v37, 1.0, v37, s[14:15]
	v_cndmask_b32_e64 v38, 1.0, v38, s[16:17]
	v_cndmask_b32_e64 v39, 1.0, v39, s[18:19]
	v_cndmask_b32_e64 v40, 1.0, v40, s[20:21]
	v_cndmask_b32_e64 v41, 1.0, v41, s[22:23]
	v_cndmask_b32_e64 v42, 1.0, v42, s[24:25]
	v_cndmask_b32_e64 v43, 1.0, v43, s[26:27]
	v_cndmask_b32_e64 v44, 1.0, v44, s[28:29]
	v_cndmask_b32_e64 v45, 1.0, v45, s[30:31]
	v_cndmask_b32_e64 v46, 1.0, v46, s[34:35]
	v_cndmask_b32_e64 v47, 1.0, v47, s[36:37]
	v_pk_mul_f32 v[230:231], v[32:33], v[34:35]
	v_mul_f32_e32 v219, v230, v231
	v_pk_mul_f32 v[230:231], v[36:37], v[38:39]
	v_mul_f32_e32 v220, v230, v231
	v_pk_mul_f32 v[230:231], v[40:41], v[42:43]
	v_mul_f32_e32 v221, v230, v231
	v_pk_mul_f32 v[230:231], v[44:45], v[46:47]
	v_mul_f32_e32 v222, v230, v231
	v_mov_b32_e32 v223, v219
	v_mov_b32_e32 v224, v220
	v_mov_b32_e32 v225, v221
	v_mov_b32_e32 v226, v222
	s_nop 1
	v_permlane32_swap_b32_e32 v219, v223
	v_permlane32_swap_b32_e32 v220, v224
	v_permlane32_swap_b32_e32 v221, v225
	v_permlane32_swap_b32_e32 v222, v226
	v_mul_f32_e32 v228, v229, v226
	v_cndmask_b32_e64 v228, v229, v228, s[2:3]
	v_mul_f32_e32 v230, v228, v47
	v_sub_f32_e32 v218, v228, v230
	v_mul_f32_e32 v228, v230, v46
	v_sub_f32_e32 v217, v230, v228
	v_mul_f32_e32 v230, v228, v45
	v_sub_f32_e32 v216, v228, v230
	v_mul_f32_e32 v228, v230, v44
	v_sub_f32_e32 v215, v230, v228
	v_mul_f32_e32 v227, v222, v226
	v_mul_f32_e32 v229, v229, v227
	v_mul_f32_e32 v228, v229, v225
	v_cndmask_b32_e64 v228, v229, v228, s[2:3]
	v_mul_f32_e32 v230, v228, v43
	v_sub_f32_e32 v214, v228, v230
	v_mul_f32_e32 v228, v230, v42
	v_sub_f32_e32 v213, v230, v228
	v_mul_f32_e32 v230, v228, v41
	v_sub_f32_e32 v212, v228, v230
	v_mul_f32_e32 v228, v230, v40
	v_sub_f32_e32 v211, v230, v228
	v_mul_f32_e32 v227, v221, v225
	v_mul_f32_e32 v229, v229, v227
	v_mul_f32_e32 v228, v229, v224
	v_cndmask_b32_e64 v228, v229, v228, s[2:3]
	v_mul_f32_e32 v230, v228, v39
	v_sub_f32_e32 v210, v228, v230
	v_mul_f32_e32 v228, v230, v38
	v_sub_f32_e32 v209, v230, v228
	v_mul_f32_e32 v230, v228, v37
	v_sub_f32_e32 v208, v228, v230
	v_mul_f32_e32 v228, v230, v36
	v_sub_f32_e32 v207, v230, v228
	v_mul_f32_e32 v227, v220, v224
	v_mul_f32_e32 v229, v229, v227
	v_mul_f32_e32 v228, v229, v223
	v_cndmask_b32_e64 v228, v229, v228, s[2:3]
	v_mul_f32_e32 v230, v228, v35
	v_sub_f32_e32 v206, v228, v230
	v_mul_f32_e32 v228, v230, v34
	v_sub_f32_e32 v205, v230, v228
	v_mul_f32_e32 v230, v228, v33
	v_sub_f32_e32 v204, v228, v230
	v_mul_f32_e32 v228, v230, v32
	v_sub_f32_e32 v203, v230, v228
	v_mul_f32_e32 v227, v219, v223
	v_mul_f32_e32 v229, v229, v227
	v_cvt_pk_bf16_f32 v176, v203, v204
	v_cvt_pk_bf16_f32 v177, v205, v206
	v_cvt_pk_bf16_f32 v178, v207, v208
	v_cvt_pk_bf16_f32 v179, v209, v210
	v_cvt_pk_bf16_f32 v180, v211, v212
	v_cvt_pk_bf16_f32 v181, v213, v214
	v_cvt_pk_bf16_f32 v182, v215, v216
	v_cvt_pk_bf16_f32 v183, v217, v218
	v_cmp_nge_f32_e32 vcc, 0x8000, v229
	s_waitcnt vmcnt(16)
	s_nop 0
	v_mfma_f32_32x32x16_bf16 v[0:15], v[80:83], v[176:179], 0
	v_mfma_f32_32x32x16_bf16 v[16:31], v[88:91], v[176:179], 0
	v_mfma_f32_32x32x16_bf16 v[0:15], v[84:87], v[180:183], v[0:15]
	v_mfma_f32_32x32x16_bf16 v[16:31], v[92:95], v[180:183], v[16:31]
	s_cmp_eq_u64 vcc, 0
	s_cbranch_scc1 .Lp6_epi
	s_cmp_eq_u32 s68, 0
	s_cbranch_scc1 .Lp6_epi
	s_add_i32 s68, s68, -1
	global_load_dwordx4 v[64:67], v185, s[74:75]
	global_load_dwordx4 v[68:71], v185, s[74:75] offset:1024
	global_load_dwordx4 v[72:75], v185, s[74:75] offset:2048
	global_load_dwordx4 v[76:79], v185, s[74:75] offset:3072
	global_load_dwordx4 v[80:83], v185, s[76:77]
	global_load_dwordx4 v[84:87], v185, s[76:77] offset:1024
	global_load_dwordx4 v[88:91], v185, s[76:77] offset:2048
	global_load_dwordx4 v[92:95], v185, s[76:77] offset:3072
; __device__ __forceinline__ void attn_phase(const Ptrs& P, int gw, int NGW, int lane) {
;     ...
;             bf16x8 k3[4], v2[2][2];
;             { const int t3 = kt > 2 ? kt - 3 : 0, t2 = kt > 1 ? kt - 2 : 0;
; #pragma unroll
;               for (int ks = 0; ks < 4; ++ks) k3[ks] = kbase[(size_t)t3 * 256 + ks * 64];
; #pragma unroll
;               for (int dt = 0; dt < 2; ++dt)
; #pragma unroll
;                   for (int s = 0; s < 2; ++s) v2[dt][s] = vbase[(size_t)t2 * 256 + (dt * 2 + s) * 64]; }
;             f32x16 sa;
; #pragma unroll
;             for (int i = 0; i < 16; ++i) sa[i] = 0.f;
; #pragma unroll
;             for (int ks = 0; ks < 4; ++ks) sa = MFMA32(kf[ks], qf[ks], sa);
;             float beta[16], f[16];
;             const bool diag = (kt == qt);
; #pragma unroll
;             for (int i = 0; i < 16; ++i) { float ff = rcpf_(1.0f + ex2(sa[i])), bt = 1.0f - ff;
;                 if (diag) { const bool valid = crow(i, hh) < r; bt = valid ? bt : 0.0f; ff = valid ? ff : 1.0f; }
;                 beta[i] = bt; f[i] = ff; }
;             float gp[4], ot[4], pr[4];
; #pragma unroll
;             for (int g = 0; g < 4; ++g) { gp[g] = (f[4 * g] * f[4 * g + 1]) * (f[4 * g + 2] * f[4 * g + 3]);
;                 const auto rr = __builtin_amdgcn_permlane32_swap(__float_as_uint(gp[g]), __float_as_uint(gp[g]), false, false);
;                 ot[g] = __uint_as_float(rr[1]); pr[g] = __uint_as_float(rr[0]) * __uint_as_float(rr[1]); }
;             float suf = Pc; float att[16];
; #pragma unroll
;             for (int g = 3; g >= 0; --g) { float p = (hh == 0) ? suf * ot[g] : suf;
;                 att[4 * g + 3] = beta[4 * g + 3] * p; p *= f[4 * g + 3];
;                 att[4 * g + 2] = beta[4 * g + 2] * p; p *= f[4 * g + 2];
;                 att[4 * g + 1] = beta[4 * g + 1] * p; p *= f[4 * g + 1];
;                 att[4 * g] = beta[4 * g] * p;
;                 suf *= pr[g]; }
;             Pc = suf;
; #pragma unroll
;             for (int i = 0; i < 16; ++i) asm("" : "+v"(att[i]));
;             bf16x8 pf[2];
; #pragma unroll
;             for (int s = 0; s < 2; ++s) { v4u t; t.x = pk2(att[8 * s], att[8 * s + 1]); t.y = pk2(att[8 * s + 2], att[8 * s + 3]); t.z = pk2(att[8 * s + 4], att[8 * s + 5]); t.w = pk2(att[8 * s + 6], att[8 * s + 7]); pf[s] = __builtin_bit_cast(bf16x8, t); }
; #pragma unroll
.Lp6_loop:
	s_waitcnt vmcnt(20)
	v_mfma_f32_32x32x16_bf16 v[32:47], v[96:99], v[48:51], 0
	v_mfma_f32_32x32x16_bf16 v[32:47], v[100:103], v[52:55], v[32:47]
	v_mfma_f32_32x32x16_bf16 v[32:47], v[104:107], v[56:59], v[32:47]
	v_mfma_f32_32x32x16_bf16 v[32:47], v[108:111], v[60:63], v[32:47]
	s_sub_i32 s80, s68, 3
	s_max_i32 s80, s80, 0
	s_lshl_b32 s80, s80, 12
	s_add_u32 s74, s70, s80
	s_addc_u32 s75, s71, 0
	s_add_u32 s76, s72, s80
	s_addc_u32 s77, s73, 0
	s_nop 4
	v_exp_f32_e32 v32, v32
	v_exp_f32_e32 v33, v33
	v_exp_f32_e32 v34, v34
	v_exp_f32_e32 v35, v35
	v_exp_f32_e32 v36, v36
	v_exp_f32_e32 v37, v37
	v_exp_f32_e32 v38, v38
	v_exp_f32_e32 v39, v39
	v_exp_f32_e32 v40, v40
	v_exp_f32_e32 v41, v41
	v_exp_f32_e32 v42, v42
	v_exp_f32_e32 v43, v43
	v_exp_f32_e32 v44, v44
	v_exp_f32_e32 v45, v45
	v_exp_f32_e32 v46, v46
	v_exp_f32_e32 v47, v47
	v_pk_add_f32 v[32:33], v[32:33], v[252:253] op_sel_hi:[1,0]
	v_pk_add_f32 v[34:35], v[34:35], v[252:253] op_sel_hi:[1,0]
	v_pk_add_f32 v[36:37], v[36:37], v[252:253] op_sel_hi:[1,0]
	v_pk_add_f32 v[38:39], v[38:39], v[252:253] op_sel_hi:[1,0]
	v_pk_add_f32 v[40:41], v[40:41], v[252:253] op_sel_hi:[1,0]
	v_pk_add_f32 v[42:43], v[42:43], v[252:253] op_sel_hi:[1,0]
	v_pk_add_f32 v[44:45], v[44:45], v[252:253] op_sel_hi:[1,0]
	v_pk_add_f32 v[46:47], v[46:47], v[252:253] op_sel_hi:[1,0]
	v_rcp_f32_e32 v32, v32
	v_rcp_f32_e32 v33, v33
	v_rcp_f32_e32 v34, v34
	v_rcp_f32_e32 v35, v35
	v_rcp_f32_e32 v36, v36
	v_rcp_f32_e32 v37, v37
	v_rcp_f32_e32 v38, v38
	v_rcp_f32_e32 v39, v39
	v_rcp_f32_e32 v40, v40
	v_rcp_f32_e32 v41, v41
	v_rcp_f32_e32 v42, v42
	v_rcp_f32_e32 v43, v43
	v_rcp_f32_e32 v44, v44
	v_rcp_f32_e32 v45, v45
	v_rcp_f32_e32 v46, v46
	v_rcp_f32_e32 v47, v47
	v_pk_mul_f32 v[230:231], v[32:33], v[34:35]
	v_mul_f32_e32 v219, v230, v231
	v_pk_mul_f32 v[230:231], v[36:37], v[38:39]
	v_mul_f32_e32 v220, v230, v231
	v_pk_mul_f32 v[230:231], v[40:41], v[42:43]
	v_mul_f32_e32 v221, v230, v231
	v_pk_mul_f32 v[230:231], v[44:45], v[46:47]
	v_mul_f32_e32 v222, v230, v231
	v_mov_b32_e32 v223, v219
	v_mov_b32_e32 v224, v220
	v_mov_b32_e32 v225, v221
	v_mov_b32_e32 v226, v222
	s_nop 1
	v_permlane32_swap_b32_e32 v219, v223
	v_permlane32_swap_b32_e32 v220, v224
	v_permlane32_swap_b32_e32 v221, v225
	v_permlane32_swap_b32_e32 v222, v226
	v_mul_f32_e32 v228, v229, v226
	v_cndmask_b32_e64 v228, v229, v228, s[2:3]
	v_mul_f32_e32 v230, v228, v47
	v_sub_f32_e32 v218, v228, v230
	v_mul_f32_e32 v228, v230, v46
	v_sub_f32_e32 v217, v230, v228
	v_mul_f32_e32 v230, v228, v45
	v_sub_f32_e32 v216, v228, v230
	v_mul_f32_e32 v228, v230, v44
	v_sub_f32_e32 v215, v230, v228
	v_mul_f32_e32 v227, v222, v226
	v_mul_f32_e32 v229, v229, v227
	v_mul_f32_e32 v228, v229, v225
	v_cndmask_b32_e64 v228, v229, v228, s[2:3]
	v_mul_f32_e32 v230, v228, v43
	v_sub_f32_e32 v214, v228, v230
	v_mul_f32_e32 v228, v230, v42
	v_sub_f32_e32 v213, v230, v228
	v_mul_f32_e32 v230, v228, v41
	v_sub_f32_e32 v212, v228, v230
	v_mul_f32_e32 v228, v230, v40
	v_sub_f32_e32 v211, v230, v228
	v_mul_f32_e32 v227, v221, v225
	v_mul_f32_e32 v229, v229, v227
	v_mul_f32_e32 v228, v229, v224
	v_cndmask_b32_e64 v228, v229, v228, s[2:3]
	v_mul_f32_e32 v230, v228, v39
	v_sub_f32_e32 v210, v228, v230
	v_mul_f32_e32 v228, v230, v38
	v_sub_f32_e32 v209, v230, v228
	v_mul_f32_e32 v230, v228, v37
	v_sub_f32_e32 v208, v228, v230
	v_mul_f32_e32 v228, v230, v36
	v_sub_f32_e32 v207, v230, v228
	v_mul_f32_e32 v227, v220, v224
	v_mul_f32_e32 v229, v229, v227
	v_mul_f32_e32 v228, v229, v223
	v_cndmask_b32_e64 v228, v229, v228, s[2:3]
	v_mul_f32_e32 v230, v228, v35
	v_sub_f32_e32 v206, v228, v230
	v_mul_f32_e32 v228, v230, v34
	v_sub_f32_e32 v205, v230, v228
	v_mul_f32_e32 v230, v228, v33
	v_sub_f32_e32 v204, v228, v230
	v_mul_f32_e32 v228, v230, v32
	v_sub_f32_e32 v203, v230, v228
	v_mul_f32_e32 v227, v219, v223
	v_mul_f32_e32 v229, v229, v227
	v_cvt_pk_bf16_f32 v176, v203, v204
	v_cvt_pk_bf16_f32 v177, v205, v206
	v_cvt_pk_bf16_f32 v178, v207, v208
	v_cvt_pk_bf16_f32 v179, v209, v210
	v_cvt_pk_bf16_f32 v180, v211, v212
	v_cvt_pk_bf16_f32 v181, v213, v214
	v_cvt_pk_bf16_f32 v182, v215, v216
	v_cvt_pk_bf16_f32 v183, v217, v218
	v_cmp_nge_f32_e32 vcc, 0x8000, v229
	s_waitcnt vmcnt(16)
	s_nop 0
	v_mfma_f32_32x32x16_bf16 v[0:15], v[112:115], v[176:179], v[0:15]
	v_mfma_f32_32x32x16_bf16 v[16:31], v[120:123], v[176:179], v[16:31]
	v_mfma_f32_32x32x16_bf16 v[0:15], v[116:119], v[180:183], v[0:15]
	v_mfma_f32_32x32x16_bf16 v[16:31], v[124:127], v[180:183], v[16:31]
	s_cmp_eq_u64 vcc, 0
	s_cbranch_scc1 .Lp6_epi
	s_cmp_eq_u32 s68, 0
	s_cbranch_scc1 .Lp6_epi
; __device__ __forceinline__ void attn_phase(const Ptrs& P, int gw, int NGW, int lane) {
;     ...
;             bf16x8 k3[4], v2[2][2];
;             { const int t3 = kt > 2 ? kt - 3 : 0, t2 = kt > 1 ? kt - 2 : 0;
; #pragma unroll
;               for (int ks = 0; ks < 4; ++ks) k3[ks] = kbase[(size_t)t3 * 256 + ks * 64];
; #pragma unroll
;               for (int dt = 0; dt < 2; ++dt)
; #pragma unroll
;                   for (int s = 0; s < 2; ++s) v2[dt][s] = vbase[(size_t)t2 * 256 + (dt * 2 + s) * 64]; }
;             f32x16 sa;
; #pragma unroll
;             for (int i = 0; i < 16; ++i) sa[i] = 0.f;
; #pragma unroll
;             for (int ks = 0; ks < 4; ++ks) sa = MFMA32(kf[ks], qf[ks], sa);
;             float beta[16], f[16];
;             const bool diag = (kt == qt);
; #pragma unroll
;             for (int i = 0; i < 16; ++i) { float ff = rcpf_(1.0f + ex2(sa[i])), bt = 1.0f - ff;
;                 if (diag) { const bool valid = crow(i, hh) < r; bt = valid ? bt : 0.0f; ff = valid ? ff : 1.0f; }
;                 beta[i] = bt; f[i] = ff; }
;             float gp[4], ot[4], pr[4];
; #pragma unroll
;             for (int g = 0; g < 4; ++g) { gp[g] = (f[4 * g] * f[4 * g + 1]) * (f[4 * g + 2] * f[4 * g + 3]);
;                 const auto rr = __builtin_amdgcn_permlane32_swap(__float_as_uint(gp[g]), __float_as_uint(gp[g]), false, false);
;                 ot[g] = __uint_as_float(rr[1]); pr[g] = __uint_as_float(rr[0]) * __uint_as_float(rr[1]); }
;             float suf = Pc; float att[16];
; #pragma unroll
;             for (int g = 3; g >= 0; --g) { float p = (hh == 0) ? suf * ot[g] : suf;
;                 att[4 * g + 3] = beta[4 * g + 3] * p; p *= f[4 * g + 3];
;                 att[4 * g + 2] = beta[4 * g + 2] * p; p *= f[4 * g + 2];
;                 att[4 * g + 1] = beta[4 * g + 1] * p; p *= f[4 * g + 1];
;                 att[4 * g] = beta[4 * g] * p;
;                 suf *= pr[g]; }
;             Pc = suf;
; #pragma unroll
;             for (int i = 0; i < 16; ++i) asm("" : "+v"(att[i]));
;             bf16x8 pf[2];
; #pragma unroll
;             for (int s = 0; s < 2; ++s) { v4u t; t.x = pk2(att[8 * s], att[8 * s + 1]); t.y = pk2(att[8 * s + 2], att[8 * s + 3]); t.z = pk2(att[8 * s + 4], att[8 * s + 5]); t.w = pk2(att[8 * s + 6], att[8 * s + 7]); pf[s] = __builtin_bit_cast(bf16x8, t); }
; #pragma unroll
	s_add_i32 s68, s68, -1
	global_load_dwordx4 v[96:99], v185, s[74:75]
	global_load_dwordx4 v[100:103], v185, s[74:75] offset:1024
	global_load_dwordx4 v[104:107], v185, s[74:75] offset:2048
	global_load_dwordx4 v[108:111], v185, s[74:75] offset:3072
	global_load_dwordx4 v[112:115], v185, s[76:77]
	global_load_dwordx4 v[116:119], v185, s[76:77] offset:1024
	global_load_dwordx4 v[120:123], v185, s[76:77] offset:2048
	global_load_dwordx4 v[124:127], v185, s[76:77] offset:3072
	s_waitcnt vmcnt(20)
	v_mfma_f32_32x32x16_bf16 v[32:47], v[128:131], v[48:51], 0
	v_mfma_f32_32x32x16_bf16 v[32:47], v[132:135], v[52:55], v[32:47]
	v_mfma_f32_32x32x16_bf16 v[32:47], v[136:139], v[56:59], v[32:47]
	v_mfma_f32_32x32x16_bf16 v[32:47], v[140:143], v[60:63], v[32:47]
	s_sub_i32 s80, s68, 3
	s_max_i32 s80, s80, 0
	s_lshl_b32 s80, s80, 12
	s_add_u32 s74, s70, s80
	s_addc_u32 s75, s71, 0
	s_add_u32 s76, s72, s80
	s_addc_u32 s77, s73, 0
	s_nop 4
	v_exp_f32_e32 v32, v32
	v_exp_f32_e32 v33, v33
	v_exp_f32_e32 v34, v34
	v_exp_f32_e32 v35, v35
	v_exp_f32_e32 v36, v36
	v_exp_f32_e32 v37, v37
	v_exp_f32_e32 v38, v38
	v_exp_f32_e32 v39, v39
	v_exp_f32_e32 v40, v40
	v_exp_f32_e32 v41, v41
	v_exp_f32_e32 v42, v42
	v_exp_f32_e32 v43, v43
	v_exp_f32_e32 v44, v44
	v_exp_f32_e32 v45, v45
	v_exp_f32_e32 v46, v46
	v_exp_f32_e32 v47, v47
	v_pk_add_f32 v[32:33], v[32:33], v[252:253] op_sel_hi:[1,0]
	v_pk_add_f32 v[34:35], v[34:35], v[252:253] op_sel_hi:[1,0]
	v_pk_add_f32 v[36:37], v[36:37], v[252:253] op_sel_hi:[1,0]
	v_pk_add_f32 v[38:39], v[38:39], v[252:253] op_sel_hi:[1,0]
	v_pk_add_f32 v[40:41], v[40:41], v[252:253] op_sel_hi:[1,0]
	v_pk_add_f32 v[42:43], v[42:43], v[252:253] op_sel_hi:[1,0]
	v_pk_add_f32 v[44:45], v[44:45], v[252:253] op_sel_hi:[1,0]
	v_pk_add_f32 v[46:47], v[46:47], v[252:253] op_sel_hi:[1,0]
	v_rcp_f32_e32 v32, v32
	v_rcp_f32_e32 v33, v33
	v_rcp_f32_e32 v34, v34
	v_rcp_f32_e32 v35, v35
	v_rcp_f32_e32 v36, v36
	v_rcp_f32_e32 v37, v37
	v_rcp_f32_e32 v38, v38
	v_rcp_f32_e32 v39, v39
	v_rcp_f32_e32 v40, v40
	v_rcp_f32_e32 v41, v41
	v_rcp_f32_e32 v42, v42
	v_rcp_f32_e32 v43, v43
	v_rcp_f32_e32 v44, v44
	v_rcp_f32_e32 v45, v45
	v_rcp_f32_e32 v46, v46
	v_rcp_f32_e32 v47, v47
	v_pk_mul_f32 v[230:231], v[32:33], v[34:35]
	v_mul_f32_e32 v219, v230, v231
	v_pk_mul_f32 v[230:231], v[36:37], v[38:39]
	v_mul_f32_e32 v220, v230, v231
	v_pk_mul_f32 v[230:231], v[40:41], v[42:43]
	v_mul_f32_e32 v221, v230, v231
	v_pk_mul_f32 v[230:231], v[44:45], v[46:47]
	v_mul_f32_e32 v222, v230, v231
	v_mov_b32_e32 v223, v219
	v_mov_b32_e32 v224, v220
	v_mov_b32_e32 v225, v221
	v_mov_b32_e32 v226, v222
	s_nop 1
	v_permlane32_swap_b32_e32 v219, v223
	v_permlane32_swap_b32_e32 v220, v224
	v_permlane32_swap_b32_e32 v221, v225
	v_permlane32_swap_b32_e32 v222, v226
	v_mul_f32_e32 v228, v229, v226
	v_cndmask_b32_e64 v228, v229, v228, s[2:3]
	v_mul_f32_e32 v230, v228, v47
	v_sub_f32_e32 v218, v228, v230
	v_mul_f32_e32 v228, v230, v46
	v_sub_f32_e32 v217, v230, v228
	v_mul_f32_e32 v230, v228, v45
	v_sub_f32_e32 v216, v228, v230
	v_mul_f32_e32 v228, v230, v44
	v_sub_f32_e32 v215, v230, v228
	v_mul_f32_e32 v227, v222, v226
	v_mul_f32_e32 v229, v229, v227
	v_mul_f32_e32 v228, v229, v225
	v_cndmask_b32_e64 v228, v229, v228, s[2:3]
	v_mul_f32_e32 v230, v228, v43
	v_sub_f32_e32 v214, v228, v230
	v_mul_f32_e32 v228, v230, v42
	v_sub_f32_e32 v213, v230, v228
	v_mul_f32_e32 v230, v228, v41
	v_sub_f32_e32 v212, v228, v230
	v_mul_f32_e32 v228, v230, v40
	v_sub_f32_e32 v211, v230, v228
	v_mul_f32_e32 v227, v221, v225
	v_mul_f32_e32 v229, v229, v227
	v_mul_f32_e32 v228, v229, v224
	v_cndmask_b32_e64 v228, v229, v228, s[2:3]
	v_mul_f32_e32 v230, v228, v39
	v_sub_f32_e32 v210, v228, v230
	v_mul_f32_e32 v228, v230, v38
	v_sub_f32_e32 v209, v230, v228
	v_mul_f32_e32 v230, v228, v37
	v_sub_f32_e32 v208, v228, v230
	v_mul_f32_e32 v228, v230, v36
	v_sub_f32_e32 v207, v230, v228
	v_mul_f32_e32 v227, v220, v224
	v_mul_f32_e32 v229, v229, v227
	v_mul_f32_e32 v228, v229, v223
	v_cndmask_b32_e64 v228, v229, v228, s[2:3]
	v_mul_f32_e32 v230, v228, v35
	v_sub_f32_e32 v206, v228, v230
	v_mul_f32_e32 v228, v230, v34
	v_sub_f32_e32 v205, v230, v228
	v_mul_f32_e32 v230, v228, v33
	v_sub_f32_e32 v204, v228, v230
	v_mul_f32_e32 v228, v230, v32
	v_sub_f32_e32 v203, v230, v228
	v_mul_f32_e32 v227, v219, v223
	v_mul_f32_e32 v229, v229, v227
	v_cvt_pk_bf16_f32 v176, v203, v204
	v_cvt_pk_bf16_f32 v177, v205, v206
	v_cvt_pk_bf16_f32 v178, v207, v208
	v_cvt_pk_bf16_f32 v179, v209, v210
	v_cvt_pk_bf16_f32 v180, v211, v212
	v_cvt_pk_bf16_f32 v181, v213, v214
	v_cvt_pk_bf16_f32 v182, v215, v216
	v_cvt_pk_bf16_f32 v183, v217, v218
	v_cmp_nge_f32_e32 vcc, 0x8000, v229
	s_waitcnt vmcnt(16)
	s_nop 0
	v_mfma_f32_32x32x16_bf16 v[0:15], v[144:147], v[176:179], v[0:15]
	v_mfma_f32_32x32x16_bf16 v[16:31], v[152:155], v[176:179], v[16:31]
	v_mfma_f32_32x32x16_bf16 v[0:15], v[148:151], v[180:183], v[0:15]
	v_mfma_f32_32x32x16_bf16 v[16:31], v[156:159], v[180:183], v[16:31]
	s_cmp_eq_u64 vcc, 0
	s_cbranch_scc1 .Lp6_epi
	s_cmp_eq_u32 s68, 0
	s_cbranch_scc1 .Lp6_epi
; __device__ __forceinline__ void attn_phase(const Ptrs& P, int gw, int NGW, int lane) {
;     ...
;             bf16x8 k3[4], v2[2][2];
;             { const int t3 = kt > 2 ? kt - 3 : 0, t2 = kt > 1 ? kt - 2 : 0;
; #pragma unroll
;               for (int ks = 0; ks < 4; ++ks) k3[ks] = kbase[(size_t)t3 * 256 + ks * 64];
; #pragma unroll
;               for (int dt = 0; dt < 2; ++dt)
; #pragma unroll
;                   for (int s = 0; s < 2; ++s) v2[dt][s] = vbase[(size_t)t2 * 256 + (dt * 2 + s) * 64]; }
;             f32x16 sa;
; #pragma unroll
;             for (int i = 0; i < 16; ++i) sa[i] = 0.f;
; #pragma unroll
;             for (int ks = 0; ks < 4; ++ks) sa = MFMA32(kf[ks], qf[ks], sa);
;             float beta[16], f[16];
;             const bool diag = (kt == qt);
; #pragma unroll
;             for (int i = 0; i < 16; ++i) { float ff = rcpf_(1.0f + ex2(sa[i])), bt = 1.0f - ff;
;                 if (diag) { const bool valid = crow(i, hh) < r; bt = valid ? bt : 0.0f; ff = valid ? ff : 1.0f; }
;                 beta[i] = bt; f[i] = ff; }
;             float gp[4], ot[4], pr[4];
; #pragma unroll
;             for (int g = 0; g < 4; ++g) { gp[g] = (f[4 * g] * f[4 * g + 1]) * (f[4 * g + 2] * f[4 * g + 3]);
;                 const auto rr = __builtin_amdgcn_permlane32_swap(__float_as_uint(gp[g]), __float_as_uint(gp[g]), false, false);
;                 ot[g] = __uint_as_float(rr[1]); pr[g] = __uint_as_float(rr[0]) * __uint_as_float(rr[1]); }
;             float suf = Pc; float att[16];
; #pragma unroll
;             for (int g = 3; g >= 0; --g) { float p = (hh == 0) ? suf * ot[g] : suf;
;                 att[4 * g + 3] = beta[4 * g + 3] * p; p *= f[4 * g + 3];
;                 att[4 * g + 2] = beta[4 * g + 2] * p; p *= f[4 * g + 2];
;                 att[4 * g + 1] = beta[4 * g + 1] * p; p *= f[4 * g + 1];
;                 att[4 * g] = beta[4 * g] * p;
;                 suf *= pr[g]; }
;             Pc = suf;
; #pragma unroll
;             for (int i = 0; i < 16; ++i) asm("" : "+v"(att[i]));
;             bf16x8 pf[2];
; #pragma unroll
;             for (int s = 0; s < 2; ++s) { v4u t; t.x = pk2(att[8 * s], att[8 * s + 1]); t.y = pk2(att[8 * s + 2], att[8 * s + 3]); t.z = pk2(att[8 * s + 4], att[8 * s + 5]); t.w = pk2(att[8 * s + 6], att[8 * s + 7]); pf[s] = __builtin_bit_cast(bf16x8, t); }
; #pragma unroll
	s_add_i32 s68, s68, -1
	global_load_dwordx4 v[128:131], v185, s[74:75]
	global_load_dwordx4 v[132:135], v185, s[74:75] offset:1024
	global_load_dwordx4 v[136:139], v185, s[74:75] offset:2048
	global_load_dwordx4 v[140:143], v185, s[74:75] offset:3072
	global_load_dwordx4 v[144:147], v185, s[76:77]
	global_load_dwordx4 v[148:151], v185, s[76:77] offset:1024
	global_load_dwordx4 v[152:155], v185, s[76:77] offset:2048
	global_load_dwordx4 v[156:159], v185, s[76:77] offset:3072
	s_waitcnt vmcnt(20)
	v_mfma_f32_32x32x16_bf16 v[32:47], v[64:67], v[48:51], 0
	v_mfma_f32_32x32x16_bf16 v[32:47], v[68:71], v[52:55], v[32:47]
	v_mfma_f32_32x32x16_bf16 v[32:47], v[72:75], v[56:59], v[32:47]
	v_mfma_f32_32x32x16_bf16 v[32:47], v[76:79], v[60:63], v[32:47]
	s_sub_i32 s80, s68, 3
	s_max_i32 s80, s80, 0
	s_lshl_b32 s80, s80, 12
	s_add_u32 s74, s70, s80
	s_addc_u32 s75, s71, 0
	s_add_u32 s76, s72, s80
	s_addc_u32 s77, s73, 0
	s_nop 4
	v_exp_f32_e32 v32, v32
	v_exp_f32_e32 v33, v33
	v_exp_f32_e32 v34, v34
	v_exp_f32_e32 v35, v35
	v_exp_f32_e32 v36, v36
	v_exp_f32_e32 v37, v37
	v_exp_f32_e32 v38, v38
	v_exp_f32_e32 v39, v39
	v_exp_f32_e32 v40, v40
	v_exp_f32_e32 v41, v41
	v_exp_f32_e32 v42, v42
	v_exp_f32_e32 v43, v43
	v_exp_f32_e32 v44, v44
	v_exp_f32_e32 v45, v45
	v_exp_f32_e32 v46, v46
	v_exp_f32_e32 v47, v47
	v_pk_add_f32 v[32:33], v[32:33], v[252:253] op_sel_hi:[1,0]
	v_pk_add_f32 v[34:35], v[34:35], v[252:253] op_sel_hi:[1,0]
	v_pk_add_f32 v[36:37], v[36:37], v[252:253] op_sel_hi:[1,0]
	v_pk_add_f32 v[38:39], v[38:39], v[252:253] op_sel_hi:[1,0]
	v_pk_add_f32 v[40:41], v[40:41], v[252:253] op_sel_hi:[1,0]
	v_pk_add_f32 v[42:43], v[42:43], v[252:253] op_sel_hi:[1,0]
	v_pk_add_f32 v[44:45], v[44:45], v[252:253] op_sel_hi:[1,0]
	v_pk_add_f32 v[46:47], v[46:47], v[252:253] op_sel_hi:[1,0]
	v_rcp_f32_e32 v32, v32
	v_rcp_f32_e32 v33, v33
	v_rcp_f32_e32 v34, v34
	v_rcp_f32_e32 v35, v35
	v_rcp_f32_e32 v36, v36
	v_rcp_f32_e32 v37, v37
	v_rcp_f32_e32 v38, v38
	v_rcp_f32_e32 v39, v39
	v_rcp_f32_e32 v40, v40
	v_rcp_f32_e32 v41, v41
	v_rcp_f32_e32 v42, v42
	v_rcp_f32_e32 v43, v43
	v_rcp_f32_e32 v44, v44
	v_rcp_f32_e32 v45, v45
	v_rcp_f32_e32 v46, v46
	v_rcp_f32_e32 v47, v47
	v_pk_mul_f32 v[230:231], v[32:33], v[34:35]
	v_mul_f32_e32 v219, v230, v231
	v_pk_mul_f32 v[230:231], v[36:37], v[38:39]
	v_mul_f32_e32 v220, v230, v231
	v_pk_mul_f32 v[230:231], v[40:41], v[42:43]
	v_mul_f32_e32 v221, v230, v231
	v_pk_mul_f32 v[230:231], v[44:45], v[46:47]
	v_mul_f32_e32 v222, v230, v231
	v_mov_b32_e32 v223, v219
	v_mov_b32_e32 v224, v220
	v_mov_b32_e32 v225, v221
	v_mov_b32_e32 v226, v222
	s_nop 1
	v_permlane32_swap_b32_e32 v219, v223
	v_permlane32_swap_b32_e32 v220, v224
	v_permlane32_swap_b32_e32 v221, v225
	v_permlane32_swap_b32_e32 v222, v226
	v_mul_f32_e32 v228, v229, v226
	v_cndmask_b32_e64 v228, v229, v228, s[2:3]
	v_mul_f32_e32 v230, v228, v47
	v_sub_f32_e32 v218, v228, v230
	v_mul_f32_e32 v228, v230, v46
	v_sub_f32_e32 v217, v230, v228
	v_mul_f32_e32 v230, v228, v45
	v_sub_f32_e32 v216, v228, v230
	v_mul_f32_e32 v228, v230, v44
	v_sub_f32_e32 v215, v230, v228
	v_mul_f32_e32 v227, v222, v226
	v_mul_f32_e32 v229, v229, v227
	v_mul_f32_e32 v228, v229, v225
	v_cndmask_b32_e64 v228, v229, v228, s[2:3]
	v_mul_f32_e32 v230, v228, v43
	v_sub_f32_e32 v214, v228, v230
	v_mul_f32_e32 v228, v230, v42
	v_sub_f32_e32 v213, v230, v228
	v_mul_f32_e32 v230, v228, v41
	v_sub_f32_e32 v212, v228, v230
	v_mul_f32_e32 v228, v230, v40
	v_sub_f32_e32 v211, v230, v228
	v_mul_f32_e32 v227, v221, v225
	v_mul_f32_e32 v229, v229, v227
	v_mul_f32_e32 v228, v229, v224
	v_cndmask_b32_e64 v228, v229, v228, s[2:3]
	v_mul_f32_e32 v230, v228, v39
	v_sub_f32_e32 v210, v228, v230
	v_mul_f32_e32 v228, v230, v38
	v_sub_f32_e32 v209, v230, v228
	v_mul_f32_e32 v230, v228, v37
	v_sub_f32_e32 v208, v228, v230
	v_mul_f32_e32 v228, v230, v36
	v_sub_f32_e32 v207, v230, v228
	v_mul_f32_e32 v227, v220, v224
	v_mul_f32_e32 v229, v229, v227
	v_mul_f32_e32 v228, v229, v223
	v_cndmask_b32_e64 v228, v229, v228, s[2:3]
	v_mul_f32_e32 v230, v228, v35
	v_sub_f32_e32 v206, v228, v230
	v_mul_f32_e32 v228, v230, v34
	v_sub_f32_e32 v205, v230, v228
	v_mul_f32_e32 v230, v228, v33
	v_sub_f32_e32 v204, v228, v230
	v_mul_f32_e32 v228, v230, v32
	v_sub_f32_e32 v203, v230, v228
	v_mul_f32_e32 v227, v219, v223
	v_mul_f32_e32 v229, v229, v227
	v_cvt_pk_bf16_f32 v176, v203, v204
	v_cvt_pk_bf16_f32 v177, v205, v206
	v_cvt_pk_bf16_f32 v178, v207, v208
	v_cvt_pk_bf16_f32 v179, v209, v210
	v_cvt_pk_bf16_f32 v180, v211, v212
	v_cvt_pk_bf16_f32 v181, v213, v214
	v_cvt_pk_bf16_f32 v182, v215, v216
	v_cvt_pk_bf16_f32 v183, v217, v218
	v_cmp_nge_f32_e32 vcc, 0x8000, v229
	s_waitcnt vmcnt(16)
	s_nop 0
	v_mfma_f32_32x32x16_bf16 v[0:15], v[80:83], v[176:179], v[0:15]
	v_mfma_f32_32x32x16_bf16 v[16:31], v[88:91], v[176:179], v[16:31]
	v_mfma_f32_32x32x16_bf16 v[0:15], v[84:87], v[180:183], v[0:15]
	v_mfma_f32_32x32x16_bf16 v[16:31], v[92:95], v[180:183], v[16:31]
	s_cmp_eq_u64 vcc, 0
	s_cbranch_scc1 .Lp6_epi
	s_cmp_eq_u32 s68, 0
	s_cbranch_scc1 .Lp6_epi
	s_add_i32 s68, s68, -1
	global_load_dwordx4 v[64:67], v185, s[74:75]
	global_load_dwordx4 v[68:71], v185, s[74:75] offset:1024
	global_load_dwordx4 v[72:75], v185, s[74:75] offset:2048
	global_load_dwordx4 v[76:79], v185, s[74:75] offset:3072
	global_load_dwordx4 v[80:83], v185, s[76:77]
	global_load_dwordx4 v[84:87], v185, s[76:77] offset:1024
	global_load_dwordx4 v[88:91], v185, s[76:77] offset:2048
	global_load_dwordx4 v[92:95], v185, s[76:77] offset:3072
	s_branch .Lp6_loop
